# attention phase: waves 0-3 at static s_setprio 3 (reset at phase end); stacked on v21
# speedup vs baseline: 1.0007x; 1.0007x over previous
; #define LAS __attribute__((address_space(3)))
; __device__ __forceinline__ unsigned xb_xcc_id() { return (unsigned)__builtin_amdgcn_s_getreg((3 << 11) | 20) & 0xFu; }
; __device__ __forceinline__ void attn_phase(LAS unsigned char* lds, const Args& a, int layer, int vcu, int G) {
;     int lane0_ = threadIdx.x & 63; asm volatile("" : "+v"(lane0_)); const int lane = lane0_;
;     const bf16* QK = (const bf16*)(a.ws + WS_QK); const bf16* VT = (const bf16*)(a.ws + WS_VT); bf16* Y = (bf16*)(a.ws + WS_Y); const float* logf = (const float*)(a.ws + WS_LOGF);
;     const float lam_init = 0.8f - 0.6f * expf(-0.3f * (float)layer);
;     const float s1 = wave_sum(a.in[4][layer * 64 + lane] * a.in[5][layer * 64 + lane]), s2 = wave_sum(a.in[6][layer * 64 + lane] * a.in[7][layer * 64 + lane]);
;     const float lam = __int_as_float(__builtin_amdgcn_readfirstlane(__float_as_int(expf(s1) - expf(s2) + lam_init))), subfac = 1.0f - lam_init;
;     const float* subg = a.in[8] + layer * 128; const float* sinks = a.in[9] + layer * 8;
;     const float* kabs = (const float*)a.ws;
;     unsigned* qctr = (unsigned*)(a.ws + 32768);
;     LAS unsigned* qslot = (LAS unsigned*)(lds + LDS_BYTES - 128);
;     const int qb0 = (int)(xb_xcc_id() & 7u);
.LBB0_227:
	v_readfirstlane_b32 s99, v196
	s_lshr_b32 s99, s99, 8
	s_cbranch_scc1 .Lprio_skip
	s_setprio 3
